# nt (streaming) hint on the read-once side-buffer loads of the hand-written P2a fix-up and P6b blocks
# baseline (speedup 1.0000x reference)
; __global__ void __launch_bounds__(NTHR, 2) hybrid_block_fwd(Args a) {
;     ...
;             const int c4 = (idx % (LW / 4)) * 4, rr = (idx / (LW / 4)) % 3, blk = idx / (3 * (LW / 4));
;             const bool seq0 = (blk & 127) == 0; const int pb = seq0 ? blk : blk - 1; const size_t row = (size_t)blk * 64 + rr;
;             const float* H = HEADU + (size_t)blk * 3 * LW + c4; const float* T = TAILU + (size_t)pb * 3 * LW + c4;
;             const f32x4 z = (f32x4){0.f, 0.f, 0.f, 0.f};
;             const f32x4 t0 = *(const f32x4*)(T), t1 = *(const f32x4*)(T + LW), t2 = *(const f32x4*)(T + 2 * LW);
;             const f32x4 h0 = *(const f32x4*)(H), h1 = *(const f32x4*)(H + (rr >= 1 ? LW : 0)), h2 = *(const f32x4*)(H + (rr >= 2 ? 2 * LW : 0));
;             const f32x4 T0 = seq0 ? z : t0, T1 = seq0 ? z : t1, T2 = seq0 ? z : t2;
;             const f32x4 u0 = rr == 0 ? h0 : (rr == 1 ? h1 : h2);
;             const f32x4 u1 = rr == 0 ? T2 : (rr == 1 ? h0 : h1);
;             const f32x4 u2 = rr == 0 ? T1 : (rr == 1 ? T2 : h0);
;             const f32x4 u3 = rr == 0 ? T0 : (rr == 1 ? T1 : T2);
;             const f32x4 v = *(const f32x4*)(lru_conv_b + c4) + *(const f32x4*)(lru_conv_w + c4) * u3 + *(const f32x4*)(lru_conv_w + LW + c4) * u2 + *(const f32x4*)(lru_conv_w + 2 * LW + c4) * u1 + *(const f32x4*)(lru_conv_w + 3 * LW + c4) * u0;
.LBB0_460:
	v_add_co_u32_e32 v4, vcc, 0x7000, v124
	s_mov_b32 s0, 0x60000
	s_nop 0
	v_addc_co_u32_e32 v5, vcc, 0, v125, vcc
	v_cmp_gt_i32_e32 vcc, s0, v128
	global_store_dwordx4 v[4:5], v[0:3], off offset:2048 sc1
	s_and_saveexec_b64 s[6:7], vcc
	s_cbranch_execz .LBB0_465
	v_mov_b32_e32 v210, 0x2000
	v_mov_b32_e32 v211, 0x4000
	v_mov_b32_e32 v200, v128
	v_lshrrev_b32_e32 v201, 9, v200
	v_and_b32_e32 v202, 0x1ff, v200
	v_lshlrev_b32_e32 v202, 4, v202
	v_mul_u32_u24_e32 v203, 0xaaab, v201
	v_lshrrev_b32_e32 v203, 17, v203
	v_mul_u32_u24_e32 v204, 3, v203
	v_sub_u32_e32 v204, v201, v204
	v_mov_b32_e32 v53, v204
	v_mov_b32_e32 v54, v203
	v_and_b32_e32 v205, 0x7f, v203
	v_cmp_ne_u32_e32 vcc, 0, v205
	v_mul_u32_u24_e32 v206, 0x6000, v203
	v_add_u32_e32 v206, v206, v202
	v_cndmask_b32_e64 v205, 0, 1, vcc
	v_sub_u32_e32 v205, v203, v205
	v_mul_u32_u24_e32 v207, 0x6000, v205
	v_add_u32_e32 v207, v207, v202
	global_load_dwordx4 v[8:11], v207, s[74:75] nt
	v_add_u32_e32 v208, 0x2000, v207
	global_load_dwordx4 v[12:15], v208, s[74:75] nt
	v_add_u32_e32 v209, 0x4000, v207
	global_load_dwordx4 v[16:19], v209, s[74:75] nt
	global_load_dwordx4 v[20:23], v206, s[50:51] nt
	v_cmp_lt_u32_e32 vcc, 0, v204
	s_nop 1
	v_cndmask_b32_e32 v208, 0, v210, vcc
	v_add_u32_e32 v208, v206, v208
	global_load_dwordx4 v[24:27], v208, s[50:51] nt
	v_cmp_lt_u32_e32 vcc, 1, v204
	s_nop 1
	v_cndmask_b32_e32 v209, 0, v211, vcc
	v_add_u32_e32 v209, v206, v209
	global_load_dwordx4 v[28:31], v209, s[50:51] nt
	global_load_dwordx4 v[32:35], v202, s[66:67]
	global_load_dwordx4 v[36:39], v202, s[64:65]
	global_load_dwordx4 v[40:43], v202, s[56:57]
	global_load_dwordx4 v[44:47], v202, s[60:61]
	global_load_dwordx4 v[48:51], v202, s[16:17]
	v_lshlrev_b32_e32 v208, 18, v203
	v_lshl_add_u32 v208, v204, 12, v208
	v_lshrrev_b32_e32 v209, 1, v202
	v_add_u32_e32 v52, v208, v209
	v_add_u32_e32 v200, 0x20000, v128
	v_lshrrev_b32_e32 v201, 9, v200
	v_and_b32_e32 v202, 0x1ff, v200
	v_lshlrev_b32_e32 v202, 4, v202
	v_mul_u32_u24_e32 v203, 0xaaab, v201
	v_lshrrev_b32_e32 v203, 17, v203
	v_mul_u32_u24_e32 v204, 3, v203
	v_sub_u32_e32 v204, v201, v204
	v_mov_b32_e32 v105, v204
	v_mov_b32_e32 v106, v203
	v_and_b32_e32 v205, 0x7f, v203
	v_cmp_ne_u32_e32 vcc, 0, v205
	v_mul_u32_u24_e32 v206, 0x6000, v203
	v_add_u32_e32 v206, v206, v202
	v_cndmask_b32_e64 v205, 0, 1, vcc
	v_sub_u32_e32 v205, v203, v205
	v_mul_u32_u24_e32 v207, 0x6000, v205
	v_add_u32_e32 v207, v207, v202
	global_load_dwordx4 v[60:63], v207, s[74:75] nt
	v_add_u32_e32 v208, 0x2000, v207
	global_load_dwordx4 v[64:67], v208, s[74:75] nt
	v_add_u32_e32 v209, 0x4000, v207
	global_load_dwordx4 v[68:71], v209, s[74:75] nt
	global_load_dwordx4 v[72:75], v206, s[50:51] nt
	v_cmp_lt_u32_e32 vcc, 0, v204
	s_nop 1
	v_cndmask_b32_e32 v208, 0, v210, vcc
	v_add_u32_e32 v208, v206, v208
	global_load_dwordx4 v[76:79], v208, s[50:51] nt
	v_cmp_lt_u32_e32 vcc, 1, v204
	s_nop 1
	v_cndmask_b32_e32 v209, 0, v211, vcc
	v_add_u32_e32 v209, v206, v209
	global_load_dwordx4 v[80:83], v209, s[50:51] nt
	global_load_dwordx4 v[84:87], v202, s[66:67]
	global_load_dwordx4 v[88:91], v202, s[64:65]
	global_load_dwordx4 v[92:95], v202, s[56:57]
	global_load_dwordx4 v[96:99], v202, s[60:61]
	global_load_dwordx4 v[100:103], v202, s[16:17]
	v_lshlrev_b32_e32 v208, 18, v203
	v_lshl_add_u32 v208, v204, 12, v208
	v_lshrrev_b32_e32 v209, 1, v202
	v_add_u32_e32 v104, v208, v209
	v_add_u32_e32 v200, 0x40000, v128
	v_lshrrev_b32_e32 v201, 9, v200
	v_and_b32_e32 v202, 0x1ff, v200
	v_lshlrev_b32_e32 v202, 4, v202
	v_mul_u32_u24_e32 v203, 0xaaab, v201
	v_lshrrev_b32_e32 v203, 17, v203
	v_mul_u32_u24_e32 v204, 3, v203
	v_sub_u32_e32 v204, v201, v204
	v_mov_b32_e32 v157, v204
	v_mov_b32_e32 v158, v203
	v_and_b32_e32 v205, 0x7f, v203
	v_cmp_ne_u32_e32 vcc, 0, v205
	v_mul_u32_u24_e32 v206, 0x6000, v203
	v_add_u32_e32 v206, v206, v202
	v_cndmask_b32_e64 v205, 0, 1, vcc
	v_sub_u32_e32 v205, v203, v205
	v_mul_u32_u24_e32 v207, 0x6000, v205
	v_add_u32_e32 v207, v207, v202
	global_load_dwordx4 v[112:115], v207, s[74:75] nt
	v_add_u32_e32 v208, 0x2000, v207
	global_load_dwordx4 v[116:119], v208, s[74:75] nt
	v_add_u32_e32 v209, 0x4000, v207
	global_load_dwordx4 v[120:123], v209, s[74:75] nt
	global_load_dwordx4 v[124:127], v206, s[50:51] nt
	v_cmp_lt_u32_e32 vcc, 0, v204
	s_nop 1
	v_cndmask_b32_e32 v208, 0, v210, vcc
	v_add_u32_e32 v208, v206, v208
	global_load_dwordx4 v[128:131], v208, s[50:51] nt
	v_cmp_lt_u32_e32 vcc, 1, v204
	s_nop 1
	v_cndmask_b32_e32 v209, 0, v211, vcc
	v_add_u32_e32 v209, v206, v209
	global_load_dwordx4 v[132:135], v209, s[50:51] nt
	global_load_dwordx4 v[136:139], v202, s[66:67]
	global_load_dwordx4 v[140:143], v202, s[64:65]
	global_load_dwordx4 v[144:147], v202, s[56:57]
	global_load_dwordx4 v[148:151], v202, s[60:61]
	global_load_dwordx4 v[152:155], v202, s[16:17]
	v_lshlrev_b32_e32 v208, 18, v203
	v_lshl_add_u32 v208, v204, 12, v208
	v_lshrrev_b32_e32 v209, 1, v202
	v_add_u32_e32 v156, v208, v209
	s_waitcnt vmcnt(22)
; __device__ __forceinline__ unsigned cvt_pk_bf16(float lo, float hi) { unsigned r; asm volatile("v_cvt_pk_bf16_f32 %0, %1, %2" : "=v"(r) : "v"(lo), "v"(hi)); return r; }
; __global__ void __launch_bounds__(NTHR, 2) hybrid_block_fwd(Args a) {
;     ...
;             const f32x4 h0 = *(const f32x4*)(H), h1 = *(const f32x4*)(H + (rr >= 1 ? LW : 0)), h2 = *(const f32x4*)(H + (rr >= 2 ? 2 * LW : 0));
;             const f32x4 T0 = seq0 ? z : t0, T1 = seq0 ? z : t1, T2 = seq0 ? z : t2;
;             const f32x4 u0 = rr == 0 ? h0 : (rr == 1 ? h1 : h2);
;             const f32x4 u1 = rr == 0 ? T2 : (rr == 1 ? h0 : h1);
;             const f32x4 u2 = rr == 0 ? T1 : (rr == 1 ? T2 : h0);
;             const f32x4 u3 = rr == 0 ? T0 : (rr == 1 ? T1 : T2);
;             const f32x4 v = *(const f32x4*)(lru_conv_b + c4) + *(const f32x4*)(lru_conv_w + c4) * u3 + *(const f32x4*)(lru_conv_w + LW + c4) * u2 + *(const f32x4*)(lru_conv_w + 2 * LW + c4) * u1 + *(const f32x4*)(lru_conv_w + 3 * LW + c4) * u0;
;             u32x2 w; w.x = cvt_pk_bf16(v[0], v[1]); w.y = cvt_pk_bf16(v[2], v[3]);
;             *(u32x2*)(VV + row * LW + c4) = w;
	v_and_b32_e32 v200, 0x7f, v54
	v_cmp_ne_u32_e64 s[0:1], 0, v200
	v_cmp_eq_u32_e64 s[4:5], 0, v53
	v_cmp_eq_u32_e64 s[8:9], 1, v53
	s_nop 1
	v_cndmask_b32_e64 v8, 0, v8, s[0:1]
	v_cndmask_b32_e64 v9, 0, v9, s[0:1]
	v_cndmask_b32_e64 v10, 0, v10, s[0:1]
	v_cndmask_b32_e64 v11, 0, v11, s[0:1]
	v_cndmask_b32_e64 v12, 0, v12, s[0:1]
	v_cndmask_b32_e64 v13, 0, v13, s[0:1]
	v_cndmask_b32_e64 v14, 0, v14, s[0:1]
	v_cndmask_b32_e64 v15, 0, v15, s[0:1]
	v_cndmask_b32_e64 v16, 0, v16, s[0:1]
	v_cndmask_b32_e64 v17, 0, v17, s[0:1]
	v_cndmask_b32_e64 v18, 0, v18, s[0:1]
	v_cndmask_b32_e64 v19, 0, v19, s[0:1]
	v_cndmask_b32_e64 v176, v16, v12, s[8:9]
	v_cndmask_b32_e64 v177, v17, v13, s[8:9]
	v_cndmask_b32_e64 v178, v18, v14, s[8:9]
	v_cndmask_b32_e64 v179, v19, v15, s[8:9]
	v_cndmask_b32_e64 v176, v176, v8, s[4:5]
	v_cndmask_b32_e64 v177, v177, v9, s[4:5]
	v_cndmask_b32_e64 v178, v178, v10, s[4:5]
	v_cndmask_b32_e64 v179, v179, v11, s[4:5]
	v_cndmask_b32_e64 v180, v20, v16, s[8:9]
	v_cndmask_b32_e64 v181, v21, v17, s[8:9]
	v_cndmask_b32_e64 v182, v22, v18, s[8:9]
	v_cndmask_b32_e64 v183, v23, v19, s[8:9]
	v_cndmask_b32_e64 v180, v180, v12, s[4:5]
	v_cndmask_b32_e64 v181, v181, v13, s[4:5]
	v_cndmask_b32_e64 v182, v182, v14, s[4:5]
	v_cndmask_b32_e64 v183, v183, v15, s[4:5]
	v_cndmask_b32_e64 v184, v24, v20, s[8:9]
	v_cndmask_b32_e64 v185, v25, v21, s[8:9]
	v_cndmask_b32_e64 v186, v26, v22, s[8:9]
	v_cndmask_b32_e64 v187, v27, v23, s[8:9]
	v_cndmask_b32_e64 v184, v184, v16, s[4:5]
	v_cndmask_b32_e64 v185, v185, v17, s[4:5]
	v_cndmask_b32_e64 v186, v186, v18, s[4:5]
	v_cndmask_b32_e64 v187, v187, v19, s[4:5]
	v_cndmask_b32_e64 v188, v28, v24, s[8:9]
	v_cndmask_b32_e64 v189, v29, v25, s[8:9]
	v_cndmask_b32_e64 v190, v30, v26, s[8:9]
	v_cndmask_b32_e64 v191, v31, v27, s[8:9]
	v_cndmask_b32_e64 v188, v188, v20, s[4:5]
	v_cndmask_b32_e64 v189, v189, v21, s[4:5]
	v_cndmask_b32_e64 v190, v190, v22, s[4:5]
	v_cndmask_b32_e64 v191, v191, v23, s[4:5]
	v_pk_fma_f32 v[192:193], v[176:177], v[36:37], v[32:33]
	v_pk_fma_f32 v[194:195], v[178:179], v[38:39], v[34:35]
	v_pk_fma_f32 v[192:193], v[180:181], v[40:41], v[192:193]
	v_pk_fma_f32 v[194:195], v[182:183], v[42:43], v[194:195]
	v_pk_fma_f32 v[192:193], v[184:185], v[44:45], v[192:193]
	v_pk_fma_f32 v[194:195], v[186:187], v[46:47], v[194:195]
	v_pk_fma_f32 v[192:193], v[188:189], v[48:49], v[192:193]
	v_pk_fma_f32 v[194:195], v[190:191], v[50:51], v[194:195]
	v_cvt_pk_bf16_f32 v192, v192, v193
	v_cvt_pk_bf16_f32 v193, v194, v195
	global_store_dwordx2 v52, v[192:193], s[54:55] sc1
	s_nop 1
	s_waitcnt vmcnt(12)
	v_and_b32_e32 v200, 0x7f, v106
	v_cmp_ne_u32_e64 s[0:1], 0, v200
	v_cmp_eq_u32_e64 s[4:5], 0, v105
	v_cmp_eq_u32_e64 s[8:9], 1, v105
	s_nop 1
	v_cndmask_b32_e64 v60, 0, v60, s[0:1]
	v_cndmask_b32_e64 v61, 0, v61, s[0:1]
	v_cndmask_b32_e64 v62, 0, v62, s[0:1]
	v_cndmask_b32_e64 v63, 0, v63, s[0:1]
	v_cndmask_b32_e64 v64, 0, v64, s[0:1]
	v_cndmask_b32_e64 v65, 0, v65, s[0:1]
	v_cndmask_b32_e64 v66, 0, v66, s[0:1]
	v_cndmask_b32_e64 v67, 0, v67, s[0:1]
	v_cndmask_b32_e64 v68, 0, v68, s[0:1]
	v_cndmask_b32_e64 v69, 0, v69, s[0:1]
	v_cndmask_b32_e64 v70, 0, v70, s[0:1]
	v_cndmask_b32_e64 v71, 0, v71, s[0:1]
	v_cndmask_b32_e64 v176, v68, v64, s[8:9]
	v_cndmask_b32_e64 v177, v69, v65, s[8:9]
	v_cndmask_b32_e64 v178, v70, v66, s[8:9]
	v_cndmask_b32_e64 v179, v71, v67, s[8:9]
	v_cndmask_b32_e64 v176, v176, v60, s[4:5]
	v_cndmask_b32_e64 v177, v177, v61, s[4:5]
	v_cndmask_b32_e64 v178, v178, v62, s[4:5]
	v_cndmask_b32_e64 v179, v179, v63, s[4:5]
	v_cndmask_b32_e64 v180, v72, v68, s[8:9]
	v_cndmask_b32_e64 v181, v73, v69, s[8:9]
	v_cndmask_b32_e64 v182, v74, v70, s[8:9]
	v_cndmask_b32_e64 v183, v75, v71, s[8:9]
	v_cndmask_b32_e64 v180, v180, v64, s[4:5]
	v_cndmask_b32_e64 v181, v181, v65, s[4:5]
	v_cndmask_b32_e64 v182, v182, v66, s[4:5]
	v_cndmask_b32_e64 v183, v183, v67, s[4:5]
	v_cndmask_b32_e64 v184, v76, v72, s[8:9]
	v_cndmask_b32_e64 v185, v77, v73, s[8:9]
	v_cndmask_b32_e64 v186, v78, v74, s[8:9]
	v_cndmask_b32_e64 v187, v79, v75, s[8:9]
	v_cndmask_b32_e64 v184, v184, v68, s[4:5]
	v_cndmask_b32_e64 v185, v185, v69, s[4:5]
	v_cndmask_b32_e64 v186, v186, v70, s[4:5]
	v_cndmask_b32_e64 v187, v187, v71, s[4:5]
	v_cndmask_b32_e64 v188, v80, v76, s[8:9]
	v_cndmask_b32_e64 v189, v81, v77, s[8:9]
	v_cndmask_b32_e64 v190, v82, v78, s[8:9]
	v_cndmask_b32_e64 v191, v83, v79, s[8:9]
	v_cndmask_b32_e64 v188, v188, v72, s[4:5]
	v_cndmask_b32_e64 v189, v189, v73, s[4:5]
	v_cndmask_b32_e64 v190, v190, v74, s[4:5]
	v_cndmask_b32_e64 v191, v191, v75, s[4:5]
	v_pk_fma_f32 v[192:193], v[176:177], v[88:89], v[84:85]
	v_pk_fma_f32 v[194:195], v[178:179], v[90:91], v[86:87]
	v_pk_fma_f32 v[192:193], v[180:181], v[92:93], v[192:193]
	v_pk_fma_f32 v[194:195], v[182:183], v[94:95], v[194:195]
	v_pk_fma_f32 v[192:193], v[184:185], v[96:97], v[192:193]
	v_pk_fma_f32 v[194:195], v[186:187], v[98:99], v[194:195]
	v_pk_fma_f32 v[192:193], v[188:189], v[100:101], v[192:193]
	v_pk_fma_f32 v[194:195], v[190:191], v[102:103], v[194:195]
	v_cvt_pk_bf16_f32 v192, v192, v193
	v_cvt_pk_bf16_f32 v193, v194, v195
	global_store_dwordx2 v104, v[192:193], s[54:55] sc1
	s_nop 1
	s_waitcnt vmcnt(2)
; __device__ __forceinline__ unsigned cvt_pk_bf16(float lo, float hi) { unsigned r; asm volatile("v_cvt_pk_bf16_f32 %0, %1, %2" : "=v"(r) : "v"(lo), "v"(hi)); return r; }
; __global__ void __launch_bounds__(NTHR, 2) hybrid_block_fwd(Args a) {
;     ...
;             const f32x4 h0 = *(const f32x4*)(H), h1 = *(const f32x4*)(H + (rr >= 1 ? LW : 0)), h2 = *(const f32x4*)(H + (rr >= 2 ? 2 * LW : 0));
;             const f32x4 T0 = seq0 ? z : t0, T1 = seq0 ? z : t1, T2 = seq0 ? z : t2;
;             const f32x4 u0 = rr == 0 ? h0 : (rr == 1 ? h1 : h2);
;             const f32x4 u1 = rr == 0 ? T2 : (rr == 1 ? h0 : h1);
;             const f32x4 u2 = rr == 0 ? T1 : (rr == 1 ? T2 : h0);
;             const f32x4 u3 = rr == 0 ? T0 : (rr == 1 ? T1 : T2);
;             const f32x4 v = *(const f32x4*)(lru_conv_b + c4) + *(const f32x4*)(lru_conv_w + c4) * u3 + *(const f32x4*)(lru_conv_w + LW + c4) * u2 + *(const f32x4*)(lru_conv_w + 2 * LW + c4) * u1 + *(const f32x4*)(lru_conv_w + 3 * LW + c4) * u0;
;             u32x2 w; w.x = cvt_pk_bf16(v[0], v[1]); w.y = cvt_pk_bf16(v[2], v[3]);
;             *(u32x2*)(VV + row * LW + c4) = w;
	v_and_b32_e32 v200, 0x7f, v158
	v_cmp_ne_u32_e64 s[0:1], 0, v200
	v_cmp_eq_u32_e64 s[4:5], 0, v157
	v_cmp_eq_u32_e64 s[8:9], 1, v157
	s_nop 1
	v_cndmask_b32_e64 v112, 0, v112, s[0:1]
	v_cndmask_b32_e64 v113, 0, v113, s[0:1]
	v_cndmask_b32_e64 v114, 0, v114, s[0:1]
	v_cndmask_b32_e64 v115, 0, v115, s[0:1]
	v_cndmask_b32_e64 v116, 0, v116, s[0:1]
	v_cndmask_b32_e64 v117, 0, v117, s[0:1]
	v_cndmask_b32_e64 v118, 0, v118, s[0:1]
	v_cndmask_b32_e64 v119, 0, v119, s[0:1]
	v_cndmask_b32_e64 v120, 0, v120, s[0:1]
	v_cndmask_b32_e64 v121, 0, v121, s[0:1]
	v_cndmask_b32_e64 v122, 0, v122, s[0:1]
	v_cndmask_b32_e64 v123, 0, v123, s[0:1]
	v_cndmask_b32_e64 v176, v120, v116, s[8:9]
	v_cndmask_b32_e64 v177, v121, v117, s[8:9]
	v_cndmask_b32_e64 v178, v122, v118, s[8:9]
	v_cndmask_b32_e64 v179, v123, v119, s[8:9]
	v_cndmask_b32_e64 v176, v176, v112, s[4:5]
	v_cndmask_b32_e64 v177, v177, v113, s[4:5]
	v_cndmask_b32_e64 v178, v178, v114, s[4:5]
	v_cndmask_b32_e64 v179, v179, v115, s[4:5]
	v_cndmask_b32_e64 v180, v124, v120, s[8:9]
	v_cndmask_b32_e64 v181, v125, v121, s[8:9]
	v_cndmask_b32_e64 v182, v126, v122, s[8:9]
	v_cndmask_b32_e64 v183, v127, v123, s[8:9]
	v_cndmask_b32_e64 v180, v180, v116, s[4:5]
	v_cndmask_b32_e64 v181, v181, v117, s[4:5]
	v_cndmask_b32_e64 v182, v182, v118, s[4:5]
	v_cndmask_b32_e64 v183, v183, v119, s[4:5]
	v_cndmask_b32_e64 v184, v128, v124, s[8:9]
	v_cndmask_b32_e64 v185, v129, v125, s[8:9]
	v_cndmask_b32_e64 v186, v130, v126, s[8:9]
	v_cndmask_b32_e64 v187, v131, v127, s[8:9]
	v_cndmask_b32_e64 v184, v184, v120, s[4:5]
	v_cndmask_b32_e64 v185, v185, v121, s[4:5]
	v_cndmask_b32_e64 v186, v186, v122, s[4:5]
	v_cndmask_b32_e64 v187, v187, v123, s[4:5]
	v_cndmask_b32_e64 v188, v132, v128, s[8:9]
	v_cndmask_b32_e64 v189, v133, v129, s[8:9]
	v_cndmask_b32_e64 v190, v134, v130, s[8:9]
	v_cndmask_b32_e64 v191, v135, v131, s[8:9]
	v_cndmask_b32_e64 v188, v188, v124, s[4:5]
	v_cndmask_b32_e64 v189, v189, v125, s[4:5]
	v_cndmask_b32_e64 v190, v190, v126, s[4:5]
	v_cndmask_b32_e64 v191, v191, v127, s[4:5]
	v_pk_fma_f32 v[192:193], v[176:177], v[140:141], v[136:137]
	v_pk_fma_f32 v[194:195], v[178:179], v[142:143], v[138:139]
	v_pk_fma_f32 v[192:193], v[180:181], v[144:145], v[192:193]
	v_pk_fma_f32 v[194:195], v[182:183], v[146:147], v[194:195]
	v_pk_fma_f32 v[192:193], v[184:185], v[148:149], v[192:193]
	v_pk_fma_f32 v[194:195], v[186:187], v[150:151], v[194:195]
	v_pk_fma_f32 v[192:193], v[188:189], v[152:153], v[192:193]
	v_pk_fma_f32 v[194:195], v[190:191], v[154:155], v[194:195]
	v_cvt_pk_bf16_f32 v192, v192, v193
	v_cvt_pk_bf16_f32 v193, v194, v195
	global_store_dwordx2 v156, v[192:193], s[54:55] sc1

; __global__ void __launch_bounds__(NTHR, 2) hybrid_block_fwd(Args a) {
;     ...
;         for (int idx = gtid; idx < 256 * 2 * (FF / 4); idx += NT) {
;             const int f4 = (idx % (FF / 4)) * 4, rr = (idx / (FF / 4)) & 1, blk = idx / (2 * (FF / 4));
;             const bool seq0 = (blk & 127) == 0; const size_t row = (size_t)blk * 64 + rr;
;             const f32x4 z = (f32x4){0.f, 0.f, 0.f, 0.f};
;             const f32x4 gc = *(const f32x4*)(HEADG + ((size_t)blk * 2 + rr) * FF + f4), vv = *(const f32x4*)(HEADV + ((size_t)blk * 2 + rr) * FF + f4);
;             f32x4 p1, p2;
;             if (rr == 0) { p1 = seq0 ? z : *(const f32x4*)(TAILG + ((size_t)(blk - 1) * 2 + 1) * FF + f4); p2 = seq0 ? z : *(const f32x4*)(TAILG + ((size_t)(blk - 1) * 2 + 0) * FF + f4); }
;             else { p1 = *(const f32x4*)(HEADG + ((size_t)blk * 2 + 0) * FF + f4); p2 = seq0 ? z : *(const f32x4*)(TAILG + ((size_t)(blk - 1) * 2 + 1) * FF + f4); }
;             const f32x4 cv = *(const f32x4*)(ffn_conv_b + f4) + *(const f32x4*)(ffn_conv_w + f4) * p2 + *(const f32x4*)(ffn_conv_w + FF + f4) * p1 + *(const f32x4*)(ffn_conv_w + 2 * FF + f4) * gc;
.LBB0_1002:
	s_or_b64 exec, exec, s[0:1]
	s_waitcnt lgkmcnt(0)
	v_mov_b32_e32 v0, v212
	v_readlane_b32 s0, v248, 8
	s_barrier
	s_mov_b64 s[4:5], exec
	v_add_u32_e32 v1, s0, v0
	s_mov_b32 s6, 0x2aaaaaab
	v_mul_hi_i32 v2, v1, s6
	v_ashrrev_i32_e32 v3, 8, v2
	v_lshlrev_b32_e32 v4, 4, v1
	v_mul_u32_u24_e32 v5, 0x6000, v3
	v_sub_u32_e32 v4, v4, v5
	v_mov_b32_e32 v49, v3
	v_add_u32_e32 v6, v5, v4
	v_add_u32_e32 v7, 0x2700000, v6
	global_load_dwordx4 v[16:19], v7, s[94:95] nt
	v_add_u32_e32 v7, 0x3300000, v6
	global_load_dwordx4 v[20:23], v7, s[94:95] nt
	v_and_b32_e32 v8, 1, v3
	v_max_i32_e32 v9, 1, v3
	v_add_u32_e32 v9, -1, v9
	v_mul_u32_u24_e32 v9, 0x6000, v9
	v_add_u32_e32 v9, v9, v4
	v_cmp_eq_u32_e32 vcc, 1, v8
	v_mov_b32_e32 v7, 0x1b00000
	v_mov_b32_e32 v5, 0x2700000
	v_cndmask_b32_e32 v7, v7, v5, vcc
	v_add_u32_e32 v7, v7, v9
	global_load_dwordx4 v[24:27], v7, s[94:95] nt
	v_max_i32_e32 v9, 2, v3
	v_add_u32_e32 v9, -2, v9
	v_mul_u32_u24_e32 v9, 0x6000, v9
	v_add_u32_e32 v9, v9, v4
	v_add_u32_e32 v9, 0x1b00000, v9
	global_load_dwordx4 v[28:31], v9, s[94:95] nt
	global_load_dwordx4 v[32:35], v4, s[86:87]
	global_load_dwordx4 v[36:39], v4, s[84:85]
	global_load_dwordx4 v[40:43], v4, s[16:17]
	global_load_dwordx4 v[44:47], v4, s[18:19]
	v_lshrrev_b32_e32 v5, 1, v3
	v_lshl_or_b32 v5, v5, 6, v8
	v_mul_u32_u24_e32 v5, 0x3000, v5
	v_lshrrev_b32_e32 v7, 1, v4
	v_add_u32_e32 v5, v5, v7
	v_add_u32_e32 v48, 0x12700000, v5
	v_add_u32_e32 v1, 0x20000, v1
	v_mul_hi_i32 v2, v1, s6
	v_ashrrev_i32_e32 v3, 8, v2
	v_lshlrev_b32_e32 v4, 4, v1
	v_mul_u32_u24_e32 v5, 0x6000, v3
	v_sub_u32_e32 v4, v4, v5
	v_mov_b32_e32 v83, v3
	v_add_u32_e32 v6, v5, v4
	v_add_u32_e32 v7, 0x2700000, v6
	global_load_dwordx4 v[50:53], v7, s[94:95] nt
	v_add_u32_e32 v7, 0x3300000, v6
	global_load_dwordx4 v[54:57], v7, s[94:95] nt
	v_and_b32_e32 v8, 1, v3
	v_max_i32_e32 v9, 1, v3
	v_add_u32_e32 v9, -1, v9
	v_mul_u32_u24_e32 v9, 0x6000, v9
	v_add_u32_e32 v9, v9, v4
	v_cmp_eq_u32_e32 vcc, 1, v8
	v_mov_b32_e32 v7, 0x1b00000
	v_mov_b32_e32 v5, 0x2700000
	v_cndmask_b32_e32 v7, v7, v5, vcc
	v_add_u32_e32 v7, v7, v9
	global_load_dwordx4 v[58:61], v7, s[94:95] nt
	v_max_i32_e32 v9, 2, v3
	v_add_u32_e32 v9, -2, v9
	v_mul_u32_u24_e32 v9, 0x6000, v9
	v_add_u32_e32 v9, v9, v4
	v_add_u32_e32 v9, 0x1b00000, v9
	global_load_dwordx4 v[62:65], v9, s[94:95] nt
	global_load_dwordx4 v[66:69], v4, s[86:87]
	global_load_dwordx4 v[70:73], v4, s[84:85]
	global_load_dwordx4 v[74:77], v4, s[16:17]
	global_load_dwordx4 v[78:81], v4, s[18:19]
	v_lshrrev_b32_e32 v5, 1, v3
	v_lshl_or_b32 v5, v5, 6, v8
	v_mul_u32_u24_e32 v5, 0x3000, v5
	v_lshrrev_b32_e32 v7, 1, v4
	v_add_u32_e32 v5, v5, v7
	v_add_u32_e32 v82, 0x12700000, v5
	v_add_u32_e32 v1, 0x20000, v1
	v_mul_hi_i32 v2, v1, s6
	v_ashrrev_i32_e32 v3, 8, v2
	v_lshlrev_b32_e32 v4, 4, v1
	v_mul_u32_u24_e32 v5, 0x6000, v3
	v_sub_u32_e32 v4, v4, v5
	v_mov_b32_e32 v117, v3
	v_add_u32_e32 v6, v5, v4
	v_add_u32_e32 v7, 0x2700000, v6
	global_load_dwordx4 v[84:87], v7, s[94:95] nt
	v_add_u32_e32 v7, 0x3300000, v6
	global_load_dwordx4 v[88:91], v7, s[94:95] nt
	v_and_b32_e32 v8, 1, v3
	v_max_i32_e32 v9, 1, v3
	v_add_u32_e32 v9, -1, v9
	v_mul_u32_u24_e32 v9, 0x6000, v9
	v_add_u32_e32 v9, v9, v4
	v_cmp_eq_u32_e32 vcc, 1, v8
	v_mov_b32_e32 v7, 0x1b00000
	v_mov_b32_e32 v5, 0x2700000
	v_cndmask_b32_e32 v7, v7, v5, vcc
	v_add_u32_e32 v7, v7, v9
	global_load_dwordx4 v[92:95], v7, s[94:95] nt
	v_max_i32_e32 v9, 2, v3
	v_add_u32_e32 v9, -2, v9
	v_mul_u32_u24_e32 v9, 0x6000, v9
	v_add_u32_e32 v9, v9, v4
	v_add_u32_e32 v9, 0x1b00000, v9
	global_load_dwordx4 v[96:99], v9, s[94:95] nt
	global_load_dwordx4 v[100:103], v4, s[86:87]
	global_load_dwordx4 v[104:107], v4, s[84:85]
	global_load_dwordx4 v[108:111], v4, s[16:17]
	global_load_dwordx4 v[112:115], v4, s[18:19]
	v_lshrrev_b32_e32 v5, 1, v3
	v_lshl_or_b32 v5, v5, 6, v8
	v_mul_u32_u24_e32 v5, 0x3000, v5
	v_lshrrev_b32_e32 v7, 1, v4
	v_add_u32_e32 v5, v5, v7
	v_add_u32_e32 v116, 0x12700000, v5
	v_add_u32_e32 v1, 0x20000, v1
	v_mul_hi_i32 v2, v1, s6
	v_ashrrev_i32_e32 v3, 8, v2
	v_lshlrev_b32_e32 v4, 4, v1
	v_mul_u32_u24_e32 v5, 0x6000, v3
	v_sub_u32_e32 v4, v4, v5
	v_mov_b32_e32 v151, v3
	v_add_u32_e32 v6, v5, v4
	v_add_u32_e32 v7, 0x2700000, v6
	global_load_dwordx4 v[118:121], v7, s[94:95] nt
	v_add_u32_e32 v7, 0x3300000, v6
	global_load_dwordx4 v[122:125], v7, s[94:95] nt
	v_and_b32_e32 v8, 1, v3
	v_max_i32_e32 v9, 1, v3
	v_add_u32_e32 v9, -1, v9
	v_mul_u32_u24_e32 v9, 0x6000, v9
	v_add_u32_e32 v9, v9, v4
	v_cmp_eq_u32_e32 vcc, 1, v8
	v_mov_b32_e32 v7, 0x1b00000
	v_mov_b32_e32 v5, 0x2700000
	v_cndmask_b32_e32 v7, v7, v5, vcc
	v_add_u32_e32 v7, v7, v9
	global_load_dwordx4 v[126:129], v7, s[94:95] nt
	v_max_i32_e32 v9, 2, v3
	v_add_u32_e32 v9, -2, v9
	v_mul_u32_u24_e32 v9, 0x6000, v9
	v_add_u32_e32 v9, v9, v4
	v_add_u32_e32 v9, 0x1b00000, v9
	global_load_dwordx4 v[130:133], v9, s[94:95] nt
	global_load_dwordx4 v[134:137], v4, s[86:87]
	global_load_dwordx4 v[138:141], v4, s[84:85]
	global_load_dwordx4 v[142:145], v4, s[16:17]
	global_load_dwordx4 v[146:149], v4, s[18:19]
	v_lshrrev_b32_e32 v5, 1, v3
	v_lshl_or_b32 v5, v5, 6, v8
	v_mul_u32_u24_e32 v5, 0x3000, v5
	v_lshrrev_b32_e32 v7, 1, v4
	v_add_u32_e32 v5, v5, v7
	v_add_u32_e32 v150, 0x12700000, v5
	v_add_u32_e32 v1, 0x20000, v1
	v_mul_hi_i32 v2, v1, s6
	v_ashrrev_i32_e32 v3, 8, v2
	v_lshlrev_b32_e32 v4, 4, v1
	v_mul_u32_u24_e32 v5, 0x6000, v3
	v_sub_u32_e32 v4, v4, v5
	v_mov_b32_e32 v185, v3
	v_add_u32_e32 v6, v5, v4
	v_add_u32_e32 v7, 0x2700000, v6
	global_load_dwordx4 v[152:155], v7, s[94:95] nt
	v_add_u32_e32 v7, 0x3300000, v6
	global_load_dwordx4 v[156:159], v7, s[94:95] nt
; __device__ __forceinline__ unsigned cvt_pk_bf16(float lo, float hi) { unsigned r; asm volatile("v_cvt_pk_bf16_f32 %0, %1, %2" : "=v"(r) : "v"(lo), "v"(hi)); return r; }
; __global__ void __launch_bounds__(NTHR, 2) hybrid_block_fwd(Args a) {
;     ...
;         for (int idx = gtid; idx < 256 * 2 * (FF / 4); idx += NT) {
;             const int f4 = (idx % (FF / 4)) * 4, rr = (idx / (FF / 4)) & 1, blk = idx / (2 * (FF / 4));
;             const bool seq0 = (blk & 127) == 0; const size_t row = (size_t)blk * 64 + rr;
;             const f32x4 z = (f32x4){0.f, 0.f, 0.f, 0.f};
;             const f32x4 gc = *(const f32x4*)(HEADG + ((size_t)blk * 2 + rr) * FF + f4), vv = *(const f32x4*)(HEADV + ((size_t)blk * 2 + rr) * FF + f4);
;             f32x4 p1, p2;
;             if (rr == 0) { p1 = seq0 ? z : *(const f32x4*)(TAILG + ((size_t)(blk - 1) * 2 + 1) * FF + f4); p2 = seq0 ? z : *(const f32x4*)(TAILG + ((size_t)(blk - 1) * 2 + 0) * FF + f4); }
;             else { p1 = *(const f32x4*)(HEADG + ((size_t)blk * 2 + 0) * FF + f4); p2 = seq0 ? z : *(const f32x4*)(TAILG + ((size_t)(blk - 1) * 2 + 1) * FF + f4); }
;             const f32x4 cv = *(const f32x4*)(ffn_conv_b + f4) + *(const f32x4*)(ffn_conv_w + f4) * p2 + *(const f32x4*)(ffn_conv_w + FF + f4) * p1 + *(const f32x4*)(ffn_conv_w + 2 * FF + f4) * gc;
;             u32x2 w; w.x = cvt_pk_bf16(gelu_tanh(cv[0]) * vv[0], gelu_tanh(cv[1]) * vv[1]); w.y = cvt_pk_bf16(gelu_tanh(cv[2]) * vv[2], gelu_tanh(cv[3]) * vv[3]);
;             *(u32x2*)(ACT + row * FF + f4) = w;
	v_and_b32_e32 v8, 1, v3
	v_max_i32_e32 v9, 1, v3
	v_add_u32_e32 v9, -1, v9
	v_mul_u32_u24_e32 v9, 0x6000, v9
	v_add_u32_e32 v9, v9, v4
	v_cmp_eq_u32_e32 vcc, 1, v8
	v_mov_b32_e32 v7, 0x1b00000
	v_mov_b32_e32 v5, 0x2700000
	v_cndmask_b32_e32 v7, v7, v5, vcc
	v_add_u32_e32 v7, v7, v9
	global_load_dwordx4 v[160:163], v7, s[94:95] nt
	v_max_i32_e32 v9, 2, v3
	v_add_u32_e32 v9, -2, v9
	v_mul_u32_u24_e32 v9, 0x6000, v9
	v_add_u32_e32 v9, v9, v4
	v_add_u32_e32 v9, 0x1b00000, v9
	global_load_dwordx4 v[164:167], v9, s[94:95] nt
	global_load_dwordx4 v[168:171], v4, s[86:87]
	global_load_dwordx4 v[172:175], v4, s[84:85]
	global_load_dwordx4 v[176:179], v4, s[16:17]
	global_load_dwordx4 v[180:183], v4, s[18:19]
	v_lshrrev_b32_e32 v5, 1, v3
	v_lshl_or_b32 v5, v5, 6, v8
	v_mul_u32_u24_e32 v5, 0x3000, v5
	v_lshrrev_b32_e32 v7, 1, v4
	v_add_u32_e32 v5, v5, v7
	v_add_u32_e32 v184, 0x12700000, v5
	v_add_u32_e32 v1, 0x20000, v1
	v_mul_hi_i32 v2, v1, s6
	v_ashrrev_i32_e32 v3, 8, v2
	v_lshlrev_b32_e32 v4, 4, v1
	v_mul_u32_u24_e32 v5, 0x6000, v3
	v_sub_u32_e32 v4, v4, v5
	v_mov_b32_e32 v225, v3
	v_add_u32_e32 v6, v5, v4
	v_add_u32_e32 v7, 0x2700000, v6
	global_load_dwordx4 v[186:189], v7, s[94:95] nt
	v_add_u32_e32 v7, 0x3300000, v6
	global_load_dwordx4 v[190:193], v7, s[94:95] nt
	v_and_b32_e32 v8, 1, v3
	v_max_i32_e32 v9, 1, v3
	v_add_u32_e32 v9, -1, v9
	v_mul_u32_u24_e32 v9, 0x6000, v9
	v_add_u32_e32 v9, v9, v4
	v_cmp_eq_u32_e32 vcc, 1, v8
	v_mov_b32_e32 v7, 0x1b00000
	v_mov_b32_e32 v5, 0x2700000
	v_cndmask_b32_e32 v7, v7, v5, vcc
	v_add_u32_e32 v7, v7, v9
	global_load_dwordx4 v[194:197], v7, s[94:95] nt
	v_max_i32_e32 v9, 2, v3
	v_add_u32_e32 v9, -2, v9
	v_mul_u32_u24_e32 v9, 0x6000, v9
	v_add_u32_e32 v9, v9, v4
	v_add_u32_e32 v9, 0x1b00000, v9
	global_load_dwordx4 v[198:201], v9, s[94:95] nt
	global_load_dwordx4 v[202:205], v4, s[86:87]
	global_load_dwordx4 v[206:209], v4, s[84:85]
	global_load_dwordx4 v[216:219], v4, s[16:17]
	global_load_dwordx4 v[220:223], v4, s[18:19]
	v_lshrrev_b32_e32 v5, 1, v3
	v_lshl_or_b32 v5, v5, 6, v8
	v_mul_u32_u24_e32 v5, 0x3000, v5
	v_lshrrev_b32_e32 v7, 1, v4
	v_add_u32_e32 v5, v5, v7
	v_add_u32_e32 v224, 0x12700000, v5
	v_add_u32_e32 v1, 0x20000, v1
	s_waitcnt vmcnt(40)
	v_lshrrev_b32_e32 v2, 1, v49
	v_and_b32_e32 v2, 0x7f, v2
	v_cmp_eq_u32_e32 vcc, 0, v2
	v_and_b32_e32 v3, 1, v49
	v_cmp_eq_u32_e64 s[8:9], 0, v3
	s_nop 1
	s_and_b64 s[8:9], s[8:9], vcc
	s_nop 1
	v_cndmask_b32_e64 v28, v28, 0, vcc
	v_cndmask_b32_e64 v24, v24, 0, s[8:9]
	v_cndmask_b32_e64 v29, v29, 0, vcc
	v_cndmask_b32_e64 v25, v25, 0, s[8:9]
	v_cndmask_b32_e64 v30, v30, 0, vcc
	v_cndmask_b32_e64 v26, v26, 0, s[8:9]
	v_cndmask_b32_e64 v31, v31, 0, vcc
	v_cndmask_b32_e64 v27, v27, 0, s[8:9]
	v_pk_fma_f32 v[30:31], v[30:31], v[38:39], v[34:35]
	v_pk_fma_f32 v[28:29], v[28:29], v[36:37], v[32:33]
	v_pk_fma_f32 v[26:27], v[26:27], v[42:43], v[30:31]
	v_pk_fma_f32 v[24:25], v[24:25], v[40:41], v[28:29]
	v_pk_fma_f32 v[18:19], v[18:19], v[46:47], v[26:27]
	v_pk_fma_f32 v[16:17], v[16:17], v[44:45], v[24:25]
	v_mul_f32_e32 v32, 0x3d922279, v16
	v_mul_f32_e32 v33, 0x3d922279, v17
	v_mul_f32_e32 v34, 0x3d922279, v18
	v_mul_f32_e32 v35, 0x3d922279, v19
	v_fmaak_f32 v32, v16, v32, 0x3fcc422a
	v_fmaak_f32 v33, v17, v33, 0x3fcc422a
	v_fmaak_f32 v34, v18, v34, 0x3fcc422a
	v_fmaak_f32 v35, v19, v35, 0x3fcc422a
	v_mul_f32_e32 v32, v16, v32
	v_mul_f32_e32 v33, v17, v33
	v_mul_f32_e32 v34, v18, v34
	v_mul_f32_e32 v35, v19, v35
	v_mul_f32_e32 v32, 0xbfb8aa3b, v32
	v_mul_f32_e32 v33, 0xbfb8aa3b, v33
	v_mul_f32_e32 v34, 0xbfb8aa3b, v34
	v_mul_f32_e32 v35, 0xbfb8aa3b, v35
	v_exp_f32_e32 v32, v32
	v_exp_f32_e32 v33, v33
	v_exp_f32_e32 v34, v34
	v_exp_f32_e32 v35, v35
	v_add_f32_e32 v32, 1.0, v32
	v_add_f32_e32 v33, 1.0, v33
	v_add_f32_e32 v34, 1.0, v34
	v_add_f32_e32 v35, 1.0, v35
	v_rcp_f32_e32 v32, v32
	v_rcp_f32_e32 v33, v33
	v_rcp_f32_e32 v34, v34
	v_rcp_f32_e32 v35, v35
	v_mul_f32_e32 v16, v16, v32
	v_mul_f32_e32 v17, v17, v33
	v_mul_f32_e32 v18, v18, v34
	v_mul_f32_e32 v19, v19, v35
	v_mul_f32_e32 v16, v20, v16
	v_mul_f32_e32 v17, v21, v17
	v_mul_f32_e32 v18, v22, v18
	v_mul_f32_e32 v19, v23, v19
	v_cvt_pk_bf16_f32 v16, v16, v17
	v_cvt_pk_bf16_f32 v17, v18, v19
	global_store_dwordx2 v48, v[16:17], s[94:95] sc1
	s_waitcnt vmcnt(33)
	v_lshrrev_b32_e32 v2, 1, v83
	v_and_b32_e32 v2, 0x7f, v2
	v_cmp_eq_u32_e32 vcc, 0, v2
	v_and_b32_e32 v3, 1, v83
	v_cmp_eq_u32_e64 s[8:9], 0, v3
	s_nop 1
	s_and_b64 s[8:9], s[8:9], vcc
	s_nop 1
	v_cndmask_b32_e64 v62, v62, 0, vcc
	v_cndmask_b32_e64 v58, v58, 0, s[8:9]
	v_cndmask_b32_e64 v63, v63, 0, vcc
	v_cndmask_b32_e64 v59, v59, 0, s[8:9]
	v_cndmask_b32_e64 v64, v64, 0, vcc
	v_cndmask_b32_e64 v60, v60, 0, s[8:9]
	v_cndmask_b32_e64 v65, v65, 0, vcc
	v_cndmask_b32_e64 v61, v61, 0, s[8:9]
	v_pk_fma_f32 v[64:65], v[64:65], v[72:73], v[68:69]
	v_pk_fma_f32 v[62:63], v[62:63], v[70:71], v[66:67]
	v_pk_fma_f32 v[60:61], v[60:61], v[76:77], v[64:65]
	v_pk_fma_f32 v[58:59], v[58:59], v[74:75], v[62:63]
	v_pk_fma_f32 v[52:53], v[52:53], v[80:81], v[60:61]
	v_pk_fma_f32 v[50:51], v[50:51], v[78:79], v[58:59]
	v_mul_f32_e32 v66, 0x3d922279, v50
	v_mul_f32_e32 v67, 0x3d922279, v51
	v_mul_f32_e32 v68, 0x3d922279, v52
	v_mul_f32_e32 v69, 0x3d922279, v53
	v_fmaak_f32 v66, v50, v66, 0x3fcc422a
	v_fmaak_f32 v67, v51, v67, 0x3fcc422a
	v_fmaak_f32 v68, v52, v68, 0x3fcc422a
	v_fmaak_f32 v69, v53, v69, 0x3fcc422a
	v_mul_f32_e32 v66, v50, v66
	v_mul_f32_e32 v67, v51, v67
	v_mul_f32_e32 v68, v52, v68
	v_mul_f32_e32 v69, v53, v69
	v_mul_f32_e32 v66, 0xbfb8aa3b, v66
	v_mul_f32_e32 v67, 0xbfb8aa3b, v67
	v_mul_f32_e32 v68, 0xbfb8aa3b, v68
	v_mul_f32_e32 v69, 0xbfb8aa3b, v69
	v_exp_f32_e32 v66, v66
	v_exp_f32_e32 v67, v67
	v_exp_f32_e32 v68, v68
	v_exp_f32_e32 v69, v69
	v_add_f32_e32 v66, 1.0, v66
	v_add_f32_e32 v67, 1.0, v67
	v_add_f32_e32 v68, 1.0, v68
	v_add_f32_e32 v69, 1.0, v69
	v_rcp_f32_e32 v66, v66
	v_rcp_f32_e32 v67, v67
	v_rcp_f32_e32 v68, v68
	v_rcp_f32_e32 v69, v69
	v_mul_f32_e32 v50, v50, v66
	v_mul_f32_e32 v51, v51, v67
	v_mul_f32_e32 v52, v52, v68
	v_mul_f32_e32 v53, v53, v69
	v_mul_f32_e32 v50, v54, v50
	v_mul_f32_e32 v51, v55, v51
	v_mul_f32_e32 v52, v56, v52
	v_mul_f32_e32 v53, v57, v53
	v_cvt_pk_bf16_f32 v50, v50, v51
	v_cvt_pk_bf16_f32 v51, v52, v53
	global_store_dwordx2 v82, v[50:51], s[94:95] sc1
	s_waitcnt vmcnt(26)
; __device__ __forceinline__ unsigned cvt_pk_bf16(float lo, float hi) { unsigned r; asm volatile("v_cvt_pk_bf16_f32 %0, %1, %2" : "=v"(r) : "v"(lo), "v"(hi)); return r; }
; __global__ void __launch_bounds__(NTHR, 2) hybrid_block_fwd(Args a) {
;     ...
;             const int f4 = (idx % (FF / 4)) * 4, rr = (idx / (FF / 4)) & 1, blk = idx / (2 * (FF / 4));
;             const bool seq0 = (blk & 127) == 0; const size_t row = (size_t)blk * 64 + rr;
;             const f32x4 z = (f32x4){0.f, 0.f, 0.f, 0.f};
;             const f32x4 gc = *(const f32x4*)(HEADG + ((size_t)blk * 2 + rr) * FF + f4), vv = *(const f32x4*)(HEADV + ((size_t)blk * 2 + rr) * FF + f4);
;             f32x4 p1, p2;
;             if (rr == 0) { p1 = seq0 ? z : *(const f32x4*)(TAILG + ((size_t)(blk - 1) * 2 + 1) * FF + f4); p2 = seq0 ? z : *(const f32x4*)(TAILG + ((size_t)(blk - 1) * 2 + 0) * FF + f4); }
;             else { p1 = *(const f32x4*)(HEADG + ((size_t)blk * 2 + 0) * FF + f4); p2 = seq0 ? z : *(const f32x4*)(TAILG + ((size_t)(blk - 1) * 2 + 1) * FF + f4); }
;             const f32x4 cv = *(const f32x4*)(ffn_conv_b + f4) + *(const f32x4*)(ffn_conv_w + f4) * p2 + *(const f32x4*)(ffn_conv_w + FF + f4) * p1 + *(const f32x4*)(ffn_conv_w + 2 * FF + f4) * gc;
;             u32x2 w; w.x = cvt_pk_bf16(gelu_tanh(cv[0]) * vv[0], gelu_tanh(cv[1]) * vv[1]); w.y = cvt_pk_bf16(gelu_tanh(cv[2]) * vv[2], gelu_tanh(cv[3]) * vv[3]);
;             *(u32x2*)(ACT + row * FF + f4) = w;
	v_lshrrev_b32_e32 v2, 1, v117
	v_and_b32_e32 v2, 0x7f, v2
	v_cmp_eq_u32_e32 vcc, 0, v2
	v_and_b32_e32 v3, 1, v117
	v_cmp_eq_u32_e64 s[8:9], 0, v3
	s_nop 1
	s_and_b64 s[8:9], s[8:9], vcc
	s_nop 1
	v_cndmask_b32_e64 v96, v96, 0, vcc
	v_cndmask_b32_e64 v92, v92, 0, s[8:9]
	v_cndmask_b32_e64 v97, v97, 0, vcc
	v_cndmask_b32_e64 v93, v93, 0, s[8:9]
	v_cndmask_b32_e64 v98, v98, 0, vcc
	v_cndmask_b32_e64 v94, v94, 0, s[8:9]
	v_cndmask_b32_e64 v99, v99, 0, vcc
	v_cndmask_b32_e64 v95, v95, 0, s[8:9]
	v_pk_fma_f32 v[98:99], v[98:99], v[106:107], v[102:103]
	v_pk_fma_f32 v[96:97], v[96:97], v[104:105], v[100:101]
	v_pk_fma_f32 v[94:95], v[94:95], v[110:111], v[98:99]
	v_pk_fma_f32 v[92:93], v[92:93], v[108:109], v[96:97]
	v_pk_fma_f32 v[86:87], v[86:87], v[114:115], v[94:95]
	v_pk_fma_f32 v[84:85], v[84:85], v[112:113], v[92:93]
	v_mul_f32_e32 v100, 0x3d922279, v84
	v_mul_f32_e32 v101, 0x3d922279, v85
	v_mul_f32_e32 v102, 0x3d922279, v86
	v_mul_f32_e32 v103, 0x3d922279, v87
	v_fmaak_f32 v100, v84, v100, 0x3fcc422a
	v_fmaak_f32 v101, v85, v101, 0x3fcc422a
	v_fmaak_f32 v102, v86, v102, 0x3fcc422a
	v_fmaak_f32 v103, v87, v103, 0x3fcc422a
	v_mul_f32_e32 v100, v84, v100
	v_mul_f32_e32 v101, v85, v101
	v_mul_f32_e32 v102, v86, v102
	v_mul_f32_e32 v103, v87, v103
	v_mul_f32_e32 v100, 0xbfb8aa3b, v100
	v_mul_f32_e32 v101, 0xbfb8aa3b, v101
	v_mul_f32_e32 v102, 0xbfb8aa3b, v102
	v_mul_f32_e32 v103, 0xbfb8aa3b, v103
	v_exp_f32_e32 v100, v100
	v_exp_f32_e32 v101, v101
	v_exp_f32_e32 v102, v102
	v_exp_f32_e32 v103, v103
	v_add_f32_e32 v100, 1.0, v100
	v_add_f32_e32 v101, 1.0, v101
	v_add_f32_e32 v102, 1.0, v102
	v_add_f32_e32 v103, 1.0, v103
	v_rcp_f32_e32 v100, v100
	v_rcp_f32_e32 v101, v101
	v_rcp_f32_e32 v102, v102
	v_rcp_f32_e32 v103, v103
	v_mul_f32_e32 v84, v84, v100
	v_mul_f32_e32 v85, v85, v101
	v_mul_f32_e32 v86, v86, v102
	v_mul_f32_e32 v87, v87, v103
	v_mul_f32_e32 v84, v88, v84
	v_mul_f32_e32 v85, v89, v85
	v_mul_f32_e32 v86, v90, v86
	v_mul_f32_e32 v87, v91, v87
	v_cvt_pk_bf16_f32 v84, v84, v85
	v_cvt_pk_bf16_f32 v85, v86, v87
	global_store_dwordx2 v116, v[84:85], s[94:95] sc1
	s_waitcnt vmcnt(19)
	v_lshrrev_b32_e32 v2, 1, v151
	v_and_b32_e32 v2, 0x7f, v2
	v_cmp_eq_u32_e32 vcc, 0, v2
	v_and_b32_e32 v3, 1, v151
	v_cmp_eq_u32_e64 s[8:9], 0, v3
	s_nop 1
	s_and_b64 s[8:9], s[8:9], vcc
	s_nop 1
	v_cndmask_b32_e64 v130, v130, 0, vcc
	v_cndmask_b32_e64 v126, v126, 0, s[8:9]
	v_cndmask_b32_e64 v131, v131, 0, vcc
	v_cndmask_b32_e64 v127, v127, 0, s[8:9]
	v_cndmask_b32_e64 v132, v132, 0, vcc
	v_cndmask_b32_e64 v128, v128, 0, s[8:9]
	v_cndmask_b32_e64 v133, v133, 0, vcc
	v_cndmask_b32_e64 v129, v129, 0, s[8:9]
	v_pk_fma_f32 v[132:133], v[132:133], v[140:141], v[136:137]
	v_pk_fma_f32 v[130:131], v[130:131], v[138:139], v[134:135]
	v_pk_fma_f32 v[128:129], v[128:129], v[144:145], v[132:133]
	v_pk_fma_f32 v[126:127], v[126:127], v[142:143], v[130:131]
	v_pk_fma_f32 v[120:121], v[120:121], v[148:149], v[128:129]
	v_pk_fma_f32 v[118:119], v[118:119], v[146:147], v[126:127]
	v_mul_f32_e32 v134, 0x3d922279, v118
	v_mul_f32_e32 v135, 0x3d922279, v119
	v_mul_f32_e32 v136, 0x3d922279, v120
	v_mul_f32_e32 v137, 0x3d922279, v121
	v_fmaak_f32 v134, v118, v134, 0x3fcc422a
	v_fmaak_f32 v135, v119, v135, 0x3fcc422a
	v_fmaak_f32 v136, v120, v136, 0x3fcc422a
	v_fmaak_f32 v137, v121, v137, 0x3fcc422a
	v_mul_f32_e32 v134, v118, v134
	v_mul_f32_e32 v135, v119, v135
	v_mul_f32_e32 v136, v120, v136
	v_mul_f32_e32 v137, v121, v137
	v_mul_f32_e32 v134, 0xbfb8aa3b, v134
	v_mul_f32_e32 v135, 0xbfb8aa3b, v135
	v_mul_f32_e32 v136, 0xbfb8aa3b, v136
	v_mul_f32_e32 v137, 0xbfb8aa3b, v137
	v_exp_f32_e32 v134, v134
	v_exp_f32_e32 v135, v135
	v_exp_f32_e32 v136, v136
	v_exp_f32_e32 v137, v137
	v_add_f32_e32 v134, 1.0, v134
	v_add_f32_e32 v135, 1.0, v135
	v_add_f32_e32 v136, 1.0, v136
	v_add_f32_e32 v137, 1.0, v137
	v_rcp_f32_e32 v134, v134
	v_rcp_f32_e32 v135, v135
	v_rcp_f32_e32 v136, v136
	v_rcp_f32_e32 v137, v137
	v_mul_f32_e32 v118, v118, v134
	v_mul_f32_e32 v119, v119, v135
	v_mul_f32_e32 v120, v120, v136
	v_mul_f32_e32 v121, v121, v137
	v_mul_f32_e32 v118, v122, v118
	v_mul_f32_e32 v119, v123, v119
	v_mul_f32_e32 v120, v124, v120
	v_mul_f32_e32 v121, v125, v121
	v_cvt_pk_bf16_f32 v118, v118, v119
	v_cvt_pk_bf16_f32 v119, v120, v121
	global_store_dwordx2 v150, v[118:119], s[94:95] sc1
	s_waitcnt vmcnt(12)
; __device__ __forceinline__ unsigned cvt_pk_bf16(float lo, float hi) { unsigned r; asm volatile("v_cvt_pk_bf16_f32 %0, %1, %2" : "=v"(r) : "v"(lo), "v"(hi)); return r; }
; __global__ void __launch_bounds__(NTHR, 2) hybrid_block_fwd(Args a) {
;     ...
;             const int f4 = (idx % (FF / 4)) * 4, rr = (idx / (FF / 4)) & 1, blk = idx / (2 * (FF / 4));
;             const bool seq0 = (blk & 127) == 0; const size_t row = (size_t)blk * 64 + rr;
;             const f32x4 z = (f32x4){0.f, 0.f, 0.f, 0.f};
;             const f32x4 gc = *(const f32x4*)(HEADG + ((size_t)blk * 2 + rr) * FF + f4), vv = *(const f32x4*)(HEADV + ((size_t)blk * 2 + rr) * FF + f4);
;             f32x4 p1, p2;
;             if (rr == 0) { p1 = seq0 ? z : *(const f32x4*)(TAILG + ((size_t)(blk - 1) * 2 + 1) * FF + f4); p2 = seq0 ? z : *(const f32x4*)(TAILG + ((size_t)(blk - 1) * 2 + 0) * FF + f4); }
;             else { p1 = *(const f32x4*)(HEADG + ((size_t)blk * 2 + 0) * FF + f4); p2 = seq0 ? z : *(const f32x4*)(TAILG + ((size_t)(blk - 1) * 2 + 1) * FF + f4); }
;             const f32x4 cv = *(const f32x4*)(ffn_conv_b + f4) + *(const f32x4*)(ffn_conv_w + f4) * p2 + *(const f32x4*)(ffn_conv_w + FF + f4) * p1 + *(const f32x4*)(ffn_conv_w + 2 * FF + f4) * gc;
;             u32x2 w; w.x = cvt_pk_bf16(gelu_tanh(cv[0]) * vv[0], gelu_tanh(cv[1]) * vv[1]); w.y = cvt_pk_bf16(gelu_tanh(cv[2]) * vv[2], gelu_tanh(cv[3]) * vv[3]);
;             *(u32x2*)(ACT + row * FF + f4) = w;
	v_lshrrev_b32_e32 v2, 1, v185
	v_and_b32_e32 v2, 0x7f, v2
	v_cmp_eq_u32_e32 vcc, 0, v2
	v_and_b32_e32 v3, 1, v185
	v_cmp_eq_u32_e64 s[8:9], 0, v3
	s_nop 1
	s_and_b64 s[8:9], s[8:9], vcc
	s_nop 1
	v_cndmask_b32_e64 v164, v164, 0, vcc
	v_cndmask_b32_e64 v160, v160, 0, s[8:9]
	v_cndmask_b32_e64 v165, v165, 0, vcc
	v_cndmask_b32_e64 v161, v161, 0, s[8:9]
	v_cndmask_b32_e64 v166, v166, 0, vcc
	v_cndmask_b32_e64 v162, v162, 0, s[8:9]
	v_cndmask_b32_e64 v167, v167, 0, vcc
	v_cndmask_b32_e64 v163, v163, 0, s[8:9]
	v_pk_fma_f32 v[166:167], v[166:167], v[174:175], v[170:171]
	v_pk_fma_f32 v[164:165], v[164:165], v[172:173], v[168:169]
	v_pk_fma_f32 v[162:163], v[162:163], v[178:179], v[166:167]
	v_pk_fma_f32 v[160:161], v[160:161], v[176:177], v[164:165]
	v_pk_fma_f32 v[154:155], v[154:155], v[182:183], v[162:163]
	v_pk_fma_f32 v[152:153], v[152:153], v[180:181], v[160:161]
	v_mul_f32_e32 v168, 0x3d922279, v152
	v_mul_f32_e32 v169, 0x3d922279, v153
	v_mul_f32_e32 v170, 0x3d922279, v154
	v_mul_f32_e32 v171, 0x3d922279, v155
	v_fmaak_f32 v168, v152, v168, 0x3fcc422a
	v_fmaak_f32 v169, v153, v169, 0x3fcc422a
	v_fmaak_f32 v170, v154, v170, 0x3fcc422a
	v_fmaak_f32 v171, v155, v171, 0x3fcc422a
	v_mul_f32_e32 v168, v152, v168
	v_mul_f32_e32 v169, v153, v169
	v_mul_f32_e32 v170, v154, v170
	v_mul_f32_e32 v171, v155, v171
	v_mul_f32_e32 v168, 0xbfb8aa3b, v168
	v_mul_f32_e32 v169, 0xbfb8aa3b, v169
	v_mul_f32_e32 v170, 0xbfb8aa3b, v170
	v_mul_f32_e32 v171, 0xbfb8aa3b, v171
	v_exp_f32_e32 v168, v168
	v_exp_f32_e32 v169, v169
	v_exp_f32_e32 v170, v170
	v_exp_f32_e32 v171, v171
	v_add_f32_e32 v168, 1.0, v168
	v_add_f32_e32 v169, 1.0, v169
	v_add_f32_e32 v170, 1.0, v170
	v_add_f32_e32 v171, 1.0, v171
	v_rcp_f32_e32 v168, v168
	v_rcp_f32_e32 v169, v169
	v_rcp_f32_e32 v170, v170
	v_rcp_f32_e32 v171, v171
	v_mul_f32_e32 v152, v152, v168
	v_mul_f32_e32 v153, v153, v169
	v_mul_f32_e32 v154, v154, v170
	v_mul_f32_e32 v155, v155, v171
	v_mul_f32_e32 v152, v156, v152
	v_mul_f32_e32 v153, v157, v153
	v_mul_f32_e32 v154, v158, v154
	v_mul_f32_e32 v155, v159, v155
	v_cvt_pk_bf16_f32 v152, v152, v153
	v_cvt_pk_bf16_f32 v153, v154, v155
	global_store_dwordx2 v184, v[152:153], s[94:95] sc1
	s_waitcnt vmcnt(5)
	v_lshrrev_b32_e32 v2, 1, v225
	v_and_b32_e32 v2, 0x7f, v2
	v_cmp_eq_u32_e32 vcc, 0, v2
	v_and_b32_e32 v3, 1, v225
	v_cmp_eq_u32_e64 s[8:9], 0, v3
	s_nop 1
	s_and_b64 s[8:9], s[8:9], vcc
	s_nop 1
	v_cndmask_b32_e64 v198, v198, 0, vcc
	v_cndmask_b32_e64 v194, v194, 0, s[8:9]
	v_cndmask_b32_e64 v199, v199, 0, vcc
	v_cndmask_b32_e64 v195, v195, 0, s[8:9]
	v_cndmask_b32_e64 v200, v200, 0, vcc
	v_cndmask_b32_e64 v196, v196, 0, s[8:9]
	v_cndmask_b32_e64 v201, v201, 0, vcc
	v_cndmask_b32_e64 v197, v197, 0, s[8:9]
	v_pk_fma_f32 v[200:201], v[200:201], v[208:209], v[204:205]
	v_pk_fma_f32 v[198:199], v[198:199], v[206:207], v[202:203]
	v_pk_fma_f32 v[196:197], v[196:197], v[218:219], v[200:201]
	v_pk_fma_f32 v[194:195], v[194:195], v[216:217], v[198:199]
	v_pk_fma_f32 v[188:189], v[188:189], v[222:223], v[196:197]
	v_pk_fma_f32 v[186:187], v[186:187], v[220:221], v[194:195]
	v_mul_f32_e32 v202, 0x3d922279, v186
	v_mul_f32_e32 v203, 0x3d922279, v187
	v_mul_f32_e32 v204, 0x3d922279, v188
	v_mul_f32_e32 v205, 0x3d922279, v189
	v_fmaak_f32 v202, v186, v202, 0x3fcc422a
	v_fmaak_f32 v203, v187, v203, 0x3fcc422a
	v_fmaak_f32 v204, v188, v204, 0x3fcc422a
	v_fmaak_f32 v205, v189, v205, 0x3fcc422a
	v_mul_f32_e32 v202, v186, v202
	v_mul_f32_e32 v203, v187, v203
	v_mul_f32_e32 v204, v188, v204
	v_mul_f32_e32 v205, v189, v205
	v_mul_f32_e32 v202, 0xbfb8aa3b, v202
	v_mul_f32_e32 v203, 0xbfb8aa3b, v203
	v_mul_f32_e32 v204, 0xbfb8aa3b, v204
	v_mul_f32_e32 v205, 0xbfb8aa3b, v205
	v_exp_f32_e32 v202, v202
	v_exp_f32_e32 v203, v203
	v_exp_f32_e32 v204, v204
	v_exp_f32_e32 v205, v205
	v_add_f32_e32 v202, 1.0, v202
	v_add_f32_e32 v203, 1.0, v203
	v_add_f32_e32 v204, 1.0, v204
	v_add_f32_e32 v205, 1.0, v205
	v_rcp_f32_e32 v202, v202
	v_rcp_f32_e32 v203, v203
	v_rcp_f32_e32 v204, v204
	v_rcp_f32_e32 v205, v205
	v_mul_f32_e32 v186, v186, v202
	v_mul_f32_e32 v187, v187, v203
	v_mul_f32_e32 v188, v188, v204
	v_mul_f32_e32 v189, v189, v205
	v_mul_f32_e32 v186, v190, v186
	v_mul_f32_e32 v187, v191, v187
	v_mul_f32_e32 v188, v192, v188
	v_mul_f32_e32 v189, v193, v189
	v_cvt_pk_bf16_f32 v186, v186, v187
	v_cvt_pk_bf16_f32 v187, v188, v189
	global_store_dwordx2 v224, v[186:187], s[94:95] sc1
	s_or_b64 exec, exec, s[4:5]
	s_waitcnt vmcnt(0)
	s_barrier
	v_readfirstlane_b32 s0, v212
	s_cmp_lg_u32 s0, 64
	s_cbranch_scc1 .Linv_8
	buffer_inv sc1
	s_waitcnt vmcnt(0)
